# v24 + QKV epilogue k-block-sum lane reduction via DPP row_shl adds instead of 64 serialized ds_bpermute round trips
# speedup vs baseline: 1.0119x; 1.0004x over previous
; __device__ __forceinline__ u32x4 pack8(f32x4 a, f32x4 b) { u32x4 w; w.x = cvt_pk_bf16(a[0], a[1]); w.y = cvt_pk_bf16(a[2], a[3]); w.z = cvt_pk_bf16(b[0], b[1]); w.w = cvt_pk_bf16(b[2], b[3]); return w; }
; __device__ __forceinline__ bf16x8 pack8(f32x4 a, f32x4 b) { u32x4 w = {cvtpk(a[0], a[1]), cvtpk(a[2], a[3]), cvtpk(b[0], b[1]), cvtpk(b[2], b[3])}; return *reinterpret_cast<bf16x8*>(&w); }
;     PG8_RSTD_HOOKS
;     __device__ __forceinline__ void operator()(const f32x4 (&acc)[2][2][4][2], const Unit& u, int wr, int wc, int fr, int fq, int par) const {
;     ...
; #pragma unroll
;                 for (int bj = 0; bj < 2; ++bj) {
;                     bf16_t* dst = base + ((size_t)((b * 8 + hh) * 4096 + s)) * 128 + cih0 + 32 * bj;
;                     *(u32x4*)dst = pack8(v[bj][0], v[bj][1]);
;                     cs[bj][0] += v[bj][0]; cs[bj][1] += v[bj][1];
;                 }
;             }
;         }
;         if (t == 1) {
; #pragma unroll
;             for (int bj = 0; bj < 2; ++bj)
; #pragma unroll
;                 for (int n = 0; n < 2; ++n)
; #pragma unroll
;                     for (int j = 0; j < 4; ++j) { float x = cs[bj][n][j]; x += __shfl_xor(x, 1); x += __shfl_xor(x, 2); x += __shfl_xor(x, 4); x += __shfl_xor(x, 8);
;                         if (fr == 0) atomicAdd(kmean + ((size_t)((b * 8 + hh) * 16 + blk)) * 128 + cih0 + 32 * bj + 4 * n + j, x); }
.LBB0_405:
	v_mov_b32_e32 v194, v195
	v_pk_mul_f32 v[18:19], v[14:15], v[194:195]
	v_pk_mul_f32 v[14:15], v[10:11], v[194:195]
	v_or_b32_e32 v10, 48, v202
	v_ashrrev_i32_e32 v11, 31, v10
	v_mov_b32_e32 v82, v195
	v_mov_b32_e32 v83, v195
	v_lshlrev_b64 v[10:11], 8, v[10:11]
	v_pk_mul_f32 v[16:17], v[16:17], v[82:83]
	v_pk_mul_f32 v[12:13], v[12:13], v[82:83]
	v_lshl_add_u64 v[10:11], v[196:197], 0, v[10:11]
	v_cvt_pk_bf16_f32 v82, v100, v101
	v_cvt_pk_bf16_f32 v83, v24, v25
	v_cvt_pk_bf16_f32 v84, v22, v23
	v_cvt_pk_bf16_f32 v85, v20, v21
	s_cmp_eq_u32 s90, 1
	global_store_dwordx4 v[10:11], v[82:85], off sc1
	s_nop 1
	v_cvt_pk_bf16_f32 v82, v18, v19
	v_cvt_pk_bf16_f32 v83, v16, v17
	v_cvt_pk_bf16_f32 v84, v14, v15
	v_cvt_pk_bf16_f32 v85, v12, v13
	global_store_dwordx4 v[10:11], v[82:85], off offset:64 sc1
	s_cbranch_scc0 .LBB0_439
	v_pk_add_f32 v[10:11], v[168:169], 0 op_sel_hi:[1,0]
	s_lshl_b32 s0, s0, 7
	v_pk_add_f32 v[10:11], v[10:11], v[152:153]
	s_lshl_b32 s1, s1, 4
	v_pk_add_f32 v[10:11], v[10:11], v[136:137]
	s_and_b32 s2, s2, 15
	v_pk_add_f32 v[10:11], v[10:11], v[104:105]
	s_or_b32 s0, s1, s0
	v_pk_add_f32 v[10:11], v[10:11], v[70:71]
	s_or_b32 s0, s0, s2
	v_pk_add_f32 v[10:11], v[10:11], v[54:55]
	s_ashr_i32 s1, s0, 31
	v_pk_add_f32 v[10:11], v[10:11], v[38:39]
	s_lshl_b64 s[0:1], s[0:1], 9
	v_pk_add_f32 v[38:39], v[10:11], v[100:101]
	s_nop 1
	v_add_f32_dpp v10, v38, v38 row_shl:1 row_mask:0xf bank_mask:0xf
	s_waitcnt lgkmcnt(0)
	v_mov_b32_e32 v10, v10
	s_nop 1
	v_add_f32_dpp v11, v10, v10 row_shl:2 row_mask:0xf bank_mask:0xf
	s_waitcnt lgkmcnt(0)
	v_mov_b32_e32 v10, v11
	s_nop 1
	v_add_f32_dpp v11, v10, v10 row_shl:4 row_mask:0xf bank_mask:0xf
	s_waitcnt lgkmcnt(0)
	v_mov_b32_e32 v38, v11
	s_nop 1
	v_add_f32_dpp v54, v38, v38 row_shl:8 row_mask:0xf bank_mask:0xf
	v_lshl_add_u64 v[10:11], v[186:187], 0, s[0:1]
	s_and_saveexec_b64 s[0:1], s[38:39]
	s_cbranch_execz .LBB0_408
	s_waitcnt lgkmcnt(0)
	v_mov_b32_e32 v38, v54
	global_atomic_add_f32 v[10:11], v38, off
.LBB0_408:
	s_or_b64 exec, exec, s[0:1]
	s_nop 1
	v_add_f32_dpp v38, v39, v39 row_shl:1 row_mask:0xf bank_mask:0xf
	s_waitcnt lgkmcnt(0)
	v_mov_b32_e32 v38, v38
	s_nop 1
	v_add_f32_dpp v39, v38, v38 row_shl:2 row_mask:0xf bank_mask:0xf
	s_waitcnt lgkmcnt(0)
	v_mov_b32_e32 v70, v39
	s_nop 1
	v_add_f32_dpp v71, v70, v70 row_shl:4 row_mask:0xf bank_mask:0xf
	v_pk_add_f32 v[38:39], v[170:171], 0 op_sel_hi:[1,0]
	s_nop 0
	v_pk_add_f32 v[38:39], v[38:39], v[154:155]
	s_nop 0
	v_pk_add_f32 v[38:39], v[38:39], v[138:139]
	s_nop 0
	v_pk_add_f32 v[54:55], v[38:39], v[106:107]
	s_waitcnt lgkmcnt(0)
	v_mov_b32_e32 v38, v71
	s_nop 1
	v_add_f32_dpp v39, v38, v38 row_shl:8 row_mask:0xf bank_mask:0xf
	v_pk_add_f32 v[54:55], v[54:55], v[72:73]
	s_nop 0
	v_pk_add_f32 v[54:55], v[54:55], v[56:57]
	s_nop 0
	v_pk_add_f32 v[40:41], v[54:55], v[40:41]
	s_nop 0
	v_pk_add_f32 v[24:25], v[40:41], v[24:25]
	s_and_saveexec_b64 s[0:1], s[38:39]
	s_cbranch_execz .LBB0_410
	s_waitcnt lgkmcnt(0)
	v_mov_b32_e32 v38, v39
	global_atomic_add_f32 v[10:11], v38, off offset:4
.LBB0_410:
	s_or_b64 exec, exec, s[0:1]
	s_nop 1
	v_add_f32_dpp v38, v24, v24 row_shl:1 row_mask:0xf bank_mask:0xf
	s_waitcnt lgkmcnt(0)
	v_mov_b32_e32 v24, v38
	s_nop 1
	v_add_f32_dpp v38, v24, v24 row_shl:2 row_mask:0xf bank_mask:0xf
	s_waitcnt lgkmcnt(0)
	v_mov_b32_e32 v24, v38
	s_nop 1
	v_add_f32_dpp v38, v24, v24 row_shl:4 row_mask:0xf bank_mask:0xf
	s_waitcnt lgkmcnt(0)
	v_mov_b32_e32 v24, v38
	s_nop 1
	v_add_f32_dpp v38, v24, v24 row_shl:8 row_mask:0xf bank_mask:0xf
	s_and_saveexec_b64 s[0:1], s[38:39]
	s_cbranch_execz .LBB0_412
	s_waitcnt lgkmcnt(0)
	v_mov_b32_e32 v24, v38
	global_atomic_add_f32 v[10:11], v24, off offset:8
.LBB0_412:
	s_or_b64 exec, exec, s[0:1]
	s_nop 1
	v_add_f32_dpp v24, v25, v25 row_shl:1 row_mask:0xf bank_mask:0xf
	s_waitcnt lgkmcnt(0)
	v_mov_b32_e32 v24, v24
	s_nop 1
	v_add_f32_dpp v25, v24, v24 row_shl:2 row_mask:0xf bank_mask:0xf
	s_waitcnt lgkmcnt(0)
	v_mov_b32_e32 v24, v25
	s_nop 1
	v_add_f32_dpp v25, v24, v24 row_shl:4 row_mask:0xf bank_mask:0xf
	s_waitcnt lgkmcnt(0)
	v_mov_b32_e32 v24, v25
	s_nop 1
	v_add_f32_dpp v25, v24, v24 row_shl:8 row_mask:0xf bank_mask:0xf
	s_and_saveexec_b64 s[0:1], s[38:39]
	s_cbranch_execz .LBB0_414
	s_waitcnt lgkmcnt(0)
	v_mov_b32_e32 v24, v25
	global_atomic_add_f32 v[10:11], v24, off offset:12
.LBB0_414:
	s_or_b64 exec, exec, s[0:1]
	s_waitcnt lgkmcnt(0)
	v_pk_add_f32 v[24:25], v[164:165], 0 op_sel_hi:[1,0]
	s_nop 0
	v_pk_add_f32 v[24:25], v[24:25], v[148:149]
	s_nop 0
	v_pk_add_f32 v[24:25], v[24:25], v[132:133]
	s_nop 0
	v_pk_add_f32 v[24:25], v[24:25], v[86:87]
	s_nop 0
	v_pk_add_f32 v[24:25], v[24:25], v[66:67]
	s_nop 0
	v_pk_add_f32 v[24:25], v[24:25], v[50:51]
	s_nop 0
	v_pk_add_f32 v[24:25], v[24:25], v[34:35]
	s_nop 0
	v_pk_add_f32 v[22:23], v[24:25], v[22:23]
	s_nop 1
	v_add_f32_dpp v24, v22, v22 row_shl:1 row_mask:0xf bank_mask:0xf
	s_waitcnt lgkmcnt(0)
	v_mov_b32_e32 v22, v24
	s_nop 1
	v_add_f32_dpp v24, v22, v22 row_shl:2 row_mask:0xf bank_mask:0xf
	s_waitcnt lgkmcnt(0)
	v_mov_b32_e32 v22, v24
	s_nop 1
	v_add_f32_dpp v24, v22, v22 row_shl:4 row_mask:0xf bank_mask:0xf
	s_waitcnt lgkmcnt(0)
	v_mov_b32_e32 v22, v24
	s_nop 1
	v_add_f32_dpp v24, v22, v22 row_shl:8 row_mask:0xf bank_mask:0xf
	s_and_saveexec_b64 s[0:1], s[38:39]
	s_cbranch_execz .LBB0_416
	s_waitcnt lgkmcnt(0)
	v_mov_b32_e32 v22, v24
	global_atomic_add_f32 v[10:11], v22, off offset:16
;     PG8_RSTD_HOOKS
;     __device__ __forceinline__ void operator()(const f32x4 (&acc)[2][2][4][2], const Unit& u, int wr, int wc, int fr, int fq, int par) const {
;     ...
;         if (t == 1) {
; #pragma unroll
;             for (int bj = 0; bj < 2; ++bj)
; #pragma unroll
;                 for (int n = 0; n < 2; ++n)
; #pragma unroll
;                     for (int j = 0; j < 4; ++j) { float x = cs[bj][n][j]; x += __shfl_xor(x, 1); x += __shfl_xor(x, 2); x += __shfl_xor(x, 4); x += __shfl_xor(x, 8);
;                         if (fr == 0) atomicAdd(kmean + ((size_t)((b * 8 + hh) * 16 + blk)) * 128 + cih0 + 32 * bj + 4 * n + j, x); }
.LBB0_416:
	s_or_b64 exec, exec, s[0:1]
	s_nop 1
	v_add_f32_dpp v22, v23, v23 row_shl:1 row_mask:0xf bank_mask:0xf
	s_waitcnt lgkmcnt(0)
	v_mov_b32_e32 v22, v22
	s_nop 1
	v_add_f32_dpp v23, v22, v22 row_shl:2 row_mask:0xf bank_mask:0xf
	s_waitcnt lgkmcnt(0)
	v_mov_b32_e32 v34, v23
	s_nop 1
	v_add_f32_dpp v35, v34, v34 row_shl:4 row_mask:0xf bank_mask:0xf
	v_pk_add_f32 v[22:23], v[166:167], 0 op_sel_hi:[1,0]
	s_nop 0
	v_pk_add_f32 v[22:23], v[22:23], v[150:151]
	s_nop 0
	v_pk_add_f32 v[22:23], v[22:23], v[134:135]
	s_nop 0
	v_pk_add_f32 v[24:25], v[22:23], v[88:89]
	s_waitcnt lgkmcnt(0)
	v_mov_b32_e32 v22, v35
	s_nop 1
	v_add_f32_dpp v23, v22, v22 row_shl:8 row_mask:0xf bank_mask:0xf
	v_pk_add_f32 v[24:25], v[24:25], v[68:69]
	s_nop 0
	v_pk_add_f32 v[24:25], v[24:25], v[52:53]
	s_nop 0
	v_pk_add_f32 v[24:25], v[24:25], v[36:37]
	s_nop 0
	v_pk_add_f32 v[20:21], v[24:25], v[20:21]
	s_and_saveexec_b64 s[0:1], s[38:39]
	s_cbranch_execz .LBB0_418
	s_waitcnt lgkmcnt(0)
	v_mov_b32_e32 v22, v23
	global_atomic_add_f32 v[10:11], v22, off offset:20
.LBB0_418:
	s_or_b64 exec, exec, s[0:1]
	s_nop 1
	v_add_f32_dpp v22, v20, v20 row_shl:1 row_mask:0xf bank_mask:0xf
	s_waitcnt lgkmcnt(0)
	v_mov_b32_e32 v20, v22
	s_nop 1
	v_add_f32_dpp v22, v20, v20 row_shl:2 row_mask:0xf bank_mask:0xf
	s_waitcnt lgkmcnt(0)
	v_mov_b32_e32 v20, v22
	s_nop 1
	v_add_f32_dpp v22, v20, v20 row_shl:4 row_mask:0xf bank_mask:0xf
	s_waitcnt lgkmcnt(0)
	v_mov_b32_e32 v20, v22
	s_nop 1
	v_add_f32_dpp v22, v20, v20 row_shl:8 row_mask:0xf bank_mask:0xf
	s_and_saveexec_b64 s[0:1], s[38:39]
	s_cbranch_execz .LBB0_420
	s_waitcnt lgkmcnt(0)
	v_mov_b32_e32 v20, v22
	global_atomic_add_f32 v[10:11], v20, off offset:24
.LBB0_420:
	s_or_b64 exec, exec, s[0:1]
	s_nop 1
	v_add_f32_dpp v20, v21, v21 row_shl:1 row_mask:0xf bank_mask:0xf
	s_waitcnt lgkmcnt(0)
	v_mov_b32_e32 v20, v20
	s_nop 1
	v_add_f32_dpp v21, v20, v20 row_shl:2 row_mask:0xf bank_mask:0xf
	s_waitcnt lgkmcnt(0)
	v_mov_b32_e32 v20, v21
	s_nop 1
	v_add_f32_dpp v21, v20, v20 row_shl:4 row_mask:0xf bank_mask:0xf
	s_waitcnt lgkmcnt(0)
	v_mov_b32_e32 v20, v21
	s_nop 1
	v_add_f32_dpp v21, v20, v20 row_shl:8 row_mask:0xf bank_mask:0xf
	s_and_saveexec_b64 s[0:1], s[38:39]
	s_cbranch_execz .LBB0_422
	s_waitcnt lgkmcnt(0)
	v_mov_b32_e32 v20, v21
	global_atomic_add_f32 v[10:11], v20, off offset:28
.LBB0_422:
	s_or_b64 exec, exec, s[0:1]
	s_waitcnt lgkmcnt(0)
	v_pk_add_f32 v[20:21], v[160:161], 0 op_sel_hi:[1,0]
	s_nop 0
	v_pk_add_f32 v[20:21], v[20:21], v[144:145]
	s_nop 0
	v_pk_add_f32 v[20:21], v[20:21], v[112:113]
	s_nop 0
	v_pk_add_f32 v[20:21], v[20:21], v[78:79]
	s_nop 0
	v_pk_add_f32 v[20:21], v[20:21], v[62:63]
	s_nop 0
	v_pk_add_f32 v[20:21], v[20:21], v[46:47]
	s_nop 0
	v_pk_add_f32 v[20:21], v[20:21], v[30:31]
	s_nop 0
	v_pk_add_f32 v[18:19], v[20:21], v[18:19]
	s_nop 1
	v_add_f32_dpp v20, v18, v18 row_shl:1 row_mask:0xf bank_mask:0xf
	s_waitcnt lgkmcnt(0)
	v_mov_b32_e32 v18, v20
	s_nop 1
	v_add_f32_dpp v20, v18, v18 row_shl:2 row_mask:0xf bank_mask:0xf
	s_waitcnt lgkmcnt(0)
	v_mov_b32_e32 v18, v20
	s_nop 1
	v_add_f32_dpp v20, v18, v18 row_shl:4 row_mask:0xf bank_mask:0xf
	s_waitcnt lgkmcnt(0)
	v_mov_b32_e32 v18, v20
	s_nop 1
	v_add_f32_dpp v20, v18, v18 row_shl:8 row_mask:0xf bank_mask:0xf
	s_and_saveexec_b64 s[0:1], s[38:39]
	s_cbranch_execz .LBB0_424
	s_waitcnt lgkmcnt(0)
	v_mov_b32_e32 v18, v20
	global_atomic_add_f32 v[10:11], v18, off offset:128
.LBB0_424:
	s_or_b64 exec, exec, s[0:1]
	s_nop 1
	v_add_f32_dpp v18, v19, v19 row_shl:1 row_mask:0xf bank_mask:0xf
	s_waitcnt lgkmcnt(0)
	v_mov_b32_e32 v18, v18
	s_nop 1
	v_add_f32_dpp v19, v18, v18 row_shl:2 row_mask:0xf bank_mask:0xf
	s_waitcnt lgkmcnt(0)
	v_mov_b32_e32 v22, v19
	s_nop 1
	v_add_f32_dpp v23, v22, v22 row_shl:4 row_mask:0xf bank_mask:0xf
	v_pk_add_f32 v[18:19], v[162:163], 0 op_sel_hi:[1,0]
	s_nop 0
	v_pk_add_f32 v[18:19], v[18:19], v[146:147]
	s_nop 0
	v_pk_add_f32 v[18:19], v[18:19], v[114:115]
	s_nop 0
	v_pk_add_f32 v[20:21], v[18:19], v[80:81]
	s_waitcnt lgkmcnt(0)
	v_mov_b32_e32 v18, v23
	s_nop 1
	v_add_f32_dpp v19, v18, v18 row_shl:8 row_mask:0xf bank_mask:0xf
	v_pk_add_f32 v[20:21], v[20:21], v[64:65]
	s_nop 0
	v_pk_add_f32 v[20:21], v[20:21], v[48:49]
	s_nop 0
	v_pk_add_f32 v[20:21], v[20:21], v[32:33]
	s_nop 0
	v_pk_add_f32 v[16:17], v[20:21], v[16:17]
	s_and_saveexec_b64 s[0:1], s[38:39]
	s_cbranch_execz .LBB0_426
	s_waitcnt lgkmcnt(0)
	v_mov_b32_e32 v18, v19
	global_atomic_add_f32 v[10:11], v18, off offset:132
;     PG8_RSTD_HOOKS
;     __device__ __forceinline__ void operator()(const f32x4 (&acc)[2][2][4][2], const Unit& u, int wr, int wc, int fr, int fq, int par) const {
;     ...
;         if (t == 1) {
; #pragma unroll
;             for (int bj = 0; bj < 2; ++bj)
; #pragma unroll
;                 for (int n = 0; n < 2; ++n)
; #pragma unroll
;                     for (int j = 0; j < 4; ++j) { float x = cs[bj][n][j]; x += __shfl_xor(x, 1); x += __shfl_xor(x, 2); x += __shfl_xor(x, 4); x += __shfl_xor(x, 8);
;                         if (fr == 0) atomicAdd(kmean + ((size_t)((b * 8 + hh) * 16 + blk)) * 128 + cih0 + 32 * bj + 4 * n + j, x); }
.LBB0_426:
	s_or_b64 exec, exec, s[0:1]
	s_nop 1
	v_add_f32_dpp v18, v16, v16 row_shl:1 row_mask:0xf bank_mask:0xf
	s_waitcnt lgkmcnt(0)
	v_mov_b32_e32 v16, v18
	s_nop 1
	v_add_f32_dpp v18, v16, v16 row_shl:2 row_mask:0xf bank_mask:0xf
	s_waitcnt lgkmcnt(0)
	v_mov_b32_e32 v16, v18
	s_nop 1
	v_add_f32_dpp v18, v16, v16 row_shl:4 row_mask:0xf bank_mask:0xf
	s_waitcnt lgkmcnt(0)
	v_mov_b32_e32 v16, v18
	s_nop 1
	v_add_f32_dpp v18, v16, v16 row_shl:8 row_mask:0xf bank_mask:0xf
	s_and_saveexec_b64 s[0:1], s[38:39]
	s_cbranch_execz .LBB0_428
	s_waitcnt lgkmcnt(0)
	v_mov_b32_e32 v16, v18
	global_atomic_add_f32 v[10:11], v16, off offset:136
.LBB0_428:
	s_or_b64 exec, exec, s[0:1]
	s_nop 1
	v_add_f32_dpp v16, v17, v17 row_shl:1 row_mask:0xf bank_mask:0xf
	s_waitcnt lgkmcnt(0)
	v_mov_b32_e32 v16, v16
	s_nop 1
	v_add_f32_dpp v17, v16, v16 row_shl:2 row_mask:0xf bank_mask:0xf
	s_waitcnt lgkmcnt(0)
	v_mov_b32_e32 v16, v17
	s_nop 1
	v_add_f32_dpp v17, v16, v16 row_shl:4 row_mask:0xf bank_mask:0xf
	s_waitcnt lgkmcnt(0)
	v_mov_b32_e32 v16, v17
	s_nop 1
	v_add_f32_dpp v17, v16, v16 row_shl:8 row_mask:0xf bank_mask:0xf
	s_and_saveexec_b64 s[0:1], s[38:39]
	s_cbranch_execz .LBB0_430
	s_waitcnt lgkmcnt(0)
	v_mov_b32_e32 v16, v17
	global_atomic_add_f32 v[10:11], v16, off offset:140
.LBB0_430:
	s_or_b64 exec, exec, s[0:1]
	s_waitcnt lgkmcnt(0)
	v_pk_add_f32 v[16:17], v[156:157], 0 op_sel_hi:[1,0]
	s_nop 0
	v_pk_add_f32 v[16:17], v[16:17], v[140:141]
	s_nop 0
	v_pk_add_f32 v[16:17], v[16:17], v[108:109]
	s_nop 0
	v_pk_add_f32 v[16:17], v[16:17], v[74:75]
	s_nop 0
	v_pk_add_f32 v[16:17], v[16:17], v[58:59]
	s_nop 0
	v_pk_add_f32 v[16:17], v[16:17], v[42:43]
	s_nop 0
	v_pk_add_f32 v[16:17], v[16:17], v[26:27]
	s_nop 0
	v_pk_add_f32 v[14:15], v[16:17], v[14:15]
	s_nop 1
	v_add_f32_dpp v16, v14, v14 row_shl:1 row_mask:0xf bank_mask:0xf
	s_waitcnt lgkmcnt(0)
	v_mov_b32_e32 v14, v16
	s_nop 1
	v_add_f32_dpp v16, v14, v14 row_shl:2 row_mask:0xf bank_mask:0xf
	s_waitcnt lgkmcnt(0)
	v_mov_b32_e32 v14, v16
	s_nop 1
	v_add_f32_dpp v16, v14, v14 row_shl:4 row_mask:0xf bank_mask:0xf
	s_waitcnt lgkmcnt(0)
	v_mov_b32_e32 v14, v16
	s_nop 1
	v_add_f32_dpp v16, v14, v14 row_shl:8 row_mask:0xf bank_mask:0xf
	s_and_saveexec_b64 s[0:1], s[38:39]
	s_cbranch_execz .LBB0_432
	s_waitcnt lgkmcnt(0)
	v_mov_b32_e32 v14, v16
	global_atomic_add_f32 v[10:11], v14, off offset:144
.LBB0_432:
	s_or_b64 exec, exec, s[0:1]
	s_nop 1
	v_add_f32_dpp v14, v15, v15 row_shl:1 row_mask:0xf bank_mask:0xf
	s_waitcnt lgkmcnt(0)
	v_mov_b32_e32 v14, v14
	s_nop 1
	v_add_f32_dpp v15, v14, v14 row_shl:2 row_mask:0xf bank_mask:0xf
	s_waitcnt lgkmcnt(0)
	v_mov_b32_e32 v18, v15
	s_nop 1
	v_add_f32_dpp v19, v18, v18 row_shl:4 row_mask:0xf bank_mask:0xf
	v_pk_add_f32 v[14:15], v[158:159], 0 op_sel_hi:[1,0]
	s_nop 0
	v_pk_add_f32 v[14:15], v[14:15], v[142:143]
	s_nop 0
	v_pk_add_f32 v[14:15], v[14:15], v[110:111]
	s_nop 0
	v_pk_add_f32 v[16:17], v[14:15], v[76:77]
	s_waitcnt lgkmcnt(0)
	v_mov_b32_e32 v14, v19
	s_nop 1
	v_add_f32_dpp v15, v14, v14 row_shl:8 row_mask:0xf bank_mask:0xf
	v_pk_add_f32 v[16:17], v[16:17], v[60:61]
	s_nop 0
	v_pk_add_f32 v[16:17], v[16:17], v[44:45]
	s_nop 0
	v_pk_add_f32 v[16:17], v[16:17], v[28:29]
	s_nop 0
	v_pk_add_f32 v[12:13], v[16:17], v[12:13]
	s_and_saveexec_b64 s[0:1], s[38:39]
	s_cbranch_execz .LBB0_434
	s_waitcnt lgkmcnt(0)
	v_mov_b32_e32 v14, v15
	global_atomic_add_f32 v[10:11], v14, off offset:148
.LBB0_434:
	s_or_b64 exec, exec, s[0:1]
	s_nop 1
	v_add_f32_dpp v14, v12, v12 row_shl:1 row_mask:0xf bank_mask:0xf
	s_waitcnt lgkmcnt(0)
	v_mov_b32_e32 v12, v14
	s_nop 1
	v_add_f32_dpp v14, v12, v12 row_shl:2 row_mask:0xf bank_mask:0xf
	s_waitcnt lgkmcnt(0)
	v_mov_b32_e32 v12, v14
	s_nop 1
	v_add_f32_dpp v14, v12, v12 row_shl:4 row_mask:0xf bank_mask:0xf
	s_waitcnt lgkmcnt(0)
	v_mov_b32_e32 v12, v14
	s_nop 1
	v_add_f32_dpp v14, v12, v12 row_shl:8 row_mask:0xf bank_mask:0xf
	s_and_saveexec_b64 s[0:1], s[38:39]
	s_cbranch_execz .LBB0_436
	s_waitcnt lgkmcnt(0)
	v_mov_b32_e32 v12, v14
	global_atomic_add_f32 v[10:11], v12, off offset:152
.LBB0_436:
	s_or_b64 exec, exec, s[0:1]
	s_nop 1
	v_add_f32_dpp v12, v13, v13 row_shl:1 row_mask:0xf bank_mask:0xf
	s_waitcnt lgkmcnt(0)
	v_mov_b32_e32 v12, v12
	s_nop 1
	v_add_f32_dpp v13, v12, v12 row_shl:2 row_mask:0xf bank_mask:0xf
	s_waitcnt lgkmcnt(0)
	v_mov_b32_e32 v12, v13
	s_nop 1
	v_add_f32_dpp v13, v12, v12 row_shl:4 row_mask:0xf bank_mask:0xf
	s_waitcnt lgkmcnt(0)
	v_mov_b32_e32 v12, v13
	s_nop 1
	v_add_f32_dpp v13, v12, v12 row_shl:8 row_mask:0xf bank_mask:0xf
	s_and_saveexec_b64 s[0:1], s[38:39]
	s_cbranch_execz .LBB0_438
	s_waitcnt lgkmcnt(0)
	v_mov_b32_e32 v12, v13
	global_atomic_add_f32 v[10:11], v12, off offset:156
